# rmsnorm phases (k5 all layers, k0 layers 1-3) fused into the residual GEMM epilogue via panel-local row-statistics exchange; 7 phases and grid barriers removed
# speedup vs baseline: 1.0093x; 1.0039x over previous
; __device__ __forceinline__ unsigned cvt_pk_bf16(float lo, float hi) { unsigned r; asm volatile("v_cvt_pk_bf16_f32 %0, %1, %2" : "=v"(r) : "v"(lo), "v"(hi)); return r; }
; #define PG8_BAR __builtin_amdgcn_s_barrier()
;     __device__ __forceinline__ void operator()(const f32x4 (&acc)[2][2][4][2], const Unit& u, int wr, int wc, int fr_in, int fq_in) const {
;     ...
;                 for (int m2 = 0; m2 < 2; ++m2) { const int m = 2 * mh + m2; const size_t off = off0 + (size_t)(ai * HALF + m * 16) * u.ldc;
; #pragma unroll
;                     for (int bj = 0; bj < 2; ++bj) { const f32x4 v0 = acc[ai][bj][m][0] + rv[m2][bj][0], v1 = acc[ai][bj][m][1] + rv[m2][bj][1];
;                         u32x4 w; w.x = cvt_pk_bf16(v0[0], v0[1]); w.y = cvt_pk_bf16(v0[2], v0[3]); w.z = cvt_pk_bf16(v1[0], v1[1]); w.w = cvt_pk_bf16(v1[2], v1[3]);
;                         *(u32x4*)(O + off + bj * HALF) = w; } }
;     ...
;         if (wr == 0) PG8_BAR;
;         E(acc, cur, wr, wc, fr, fq);
;         if (!has_next) break;
.LBB0_337:
	s_waitcnt vmcnt(6)
	v_pk_add_f32 v[130:131], v[46:47], v[130:131]
	v_pk_add_f32 v[128:129], v[44:45], v[128:129]
	v_lshl_add_u64 v[176:177], v[174:175], 0, s[38:39]
	v_pk_add_f32 v[142:143], v[42:43], v[142:143]
	v_pk_add_f32 v[140:141], v[40:41], v[140:141]
	v_cvt_pk_bf16_f32 v128, v128, v129
	v_cvt_pk_bf16_f32 v129, v130, v131
	s_andn2_b64 vcc, exec, s[64:65]
	v_cvt_pk_bf16_f32 v130, v140, v141
	v_cvt_pk_bf16_f32 v131, v142, v143
	global_store_dwordx4 v[176:177], v[128:131], off
	s_movk_i32 s56, 0x1f8
	s_movk_i32 s57, 0x1fff
	s_waitcnt vmcnt(5)
	v_pk_add_f32 v[130:131], v[14:15], v[134:135]
	v_pk_add_f32 v[128:129], v[12:13], v[132:133]
	v_pk_add_f32 v[132:133], v[10:11], v[150:151]
	v_pk_add_f32 v[134:135], v[8:9], v[148:149]
	v_cvt_pk_bf16_f32 v128, v128, v129
	v_cvt_pk_bf16_f32 v129, v130, v131
	s_mov_b32 s64, 0xb0000
	v_cvt_pk_bf16_f32 v130, v134, v135
	v_cvt_pk_bf16_f32 v131, v132, v133
	global_store_dwordx4 v[176:177], v[128:131], off offset:256
	v_lshl_add_u64 v[132:133], v[174:175], 0, s[0:1]
	s_waitcnt vmcnt(5)
	v_pk_add_f32 v[134:135], v[34:35], v[154:155]
	s_waitcnt vmcnt(4)
	v_pk_add_f32 v[130:131], v[38:39], v[138:139]
	v_pk_add_f32 v[128:129], v[36:37], v[136:137]
	v_pk_add_f32 v[136:137], v[32:33], v[152:153]
	v_cvt_pk_bf16_f32 v128, v128, v129
	v_cvt_pk_bf16_f32 v129, v130, v131
	s_mov_b32 s65, 0xdc000
	v_cvt_pk_bf16_f32 v130, v136, v137
	v_cvt_pk_bf16_f32 v131, v134, v135
	global_store_dwordx4 v[132:133], v[128:131], off
	s_waitcnt vmcnt(4)
	v_pk_add_f32 v[134:135], v[2:3], v[158:159]
	v_pk_add_f32 v[136:137], v[0:1], v[156:157]
	s_waitcnt vmcnt(3)
	v_pk_add_f32 v[130:131], v[6:7], v[146:147]
	v_pk_add_f32 v[128:129], v[4:5], v[144:145]
	s_nop 0
	v_cvt_pk_bf16_f32 v128, v128, v129
	v_cvt_pk_bf16_f32 v129, v130, v131
	v_cvt_pk_bf16_f32 v130, v136, v137
	v_cvt_pk_bf16_f32 v131, v134, v135
	global_store_dwordx4 v[132:133], v[128:131], off offset:256
	s_branch .Lln_begin
.Lln_ret:
	v_readlane_b32 s0, v254, 54
	v_readlane_b32 s1, v254, 55
	s_andn2_b64 vcc, exec, s[0:1]
	s_cbranch_vccnz .LBB0_281
	s_barrier
	s_branch .LBB0_281

; __device__ __forceinline__ void xcd_barrier(const XcdBarrier& b) {
;     asm volatile("s_waitcnt vmcnt(0)" ::: "memory");
;     __syncthreads();
;     if (threadIdx.x == 0) {
;         unsigned* bar = b.bar;
;         __builtin_amdgcn_s_waitcnt(0);
;         unsigned nloc = b.st[0], nx = b.st[1];
;         if (nloc == 0u) { xcd_barrier_complete(bar, b.x, nloc, nx); b.st[0] = nloc; b.st[1] = nx; }
; __global__ void __launch_bounds__(NTHREADS) fwd_megakernel(Params p) {
;     ...
;         if (ph + 1 < p.ph_hi && need_bar) { if (p.ph_lo < 0) cg::this_grid().sync(); else xcd_barrier(gbar); }
.LBB0_611:
	s_or_b64 exec, exec, s[2:3]
	s_mov_b64 s[6:7], -1
.LBB0_612:
	s_branch .Lln_latch
.Lln_latch_ret:
	s_cmp_ge_i32 s90, s91
	s_cselect_b64 s[0:1], -1, 0
	s_cmp_lt_i32 s90, s91
	s_cselect_b64 s[2:3], -1, 0
	s_and_b64 s[2:3], s[2:3], s[6:7]
	s_andn2_b64 vcc, exec, s[2:3]
	s_cbranch_vccnz .LBB0_10
	v_readlane_b32 s6, v252, 34
	v_readlane_b32 s7, v252, 35
	s_mov_b64 s[2:3], -1
	s_and_b64 vcc, exec, s[6:7]
	s_cbranch_vccz .LBB0_668
	s_waitcnt vmcnt(0)
	s_waitcnt vmcnt(0) lgkmcnt(0)
	s_barrier
	s_mov_b64 s[2:3], exec
	v_readlane_b32 s6, v252, 0
	v_readlane_b32 s7, v252, 1
	s_and_b64 s[6:7], s[2:3], s[6:7]
	s_mov_b64 exec, s[6:7]
	s_cbranch_execz .LBB0_667
	v_readlane_b32 s6, v253, 51
	s_waitcnt vmcnt(0) expcnt(0) lgkmcnt(0)
	s_nop 0
	v_mov_b32_e32 v0, s6
	ds_read_b32 v2, v0
	v_readlane_b32 s6, v253, 52
	s_waitcnt lgkmcnt(0)
	v_cmp_ne_u32_e32 vcc, 0, v2
	v_mov_b32_e32 v0, s6
	ds_read_b32 v0, v0
	s_cbranch_vccnz .LBB0_630
	v_readlane_b32 s8, v252, 2
	v_readlane_b32 s9, v252, 3
	s_load_dwordx2 s[6:7], s[8:9], 0x0
	s_nop 0
	s_load_dword s8, s[8:9], 0x8
	s_mov_b32 s13, 1
	s_waitcnt lgkmcnt(0)
	s_mul_i32 s12, s7, s6
	s_mul_i32 s12, s12, s8
	s_branch .LBB0_618

; __device__ __forceinline__ float bflo(unsigned w) { return __uint_as_float(w << 16); }
; __device__ __forceinline__ float bfhi(unsigned w) { return __uint_as_float(w & 0xffff0000u); }
; __device__ __forceinline__ int opaque_tid() { int t = threadIdx.x; asm volatile("" : "+v"(t)); return t; }
; __device__ __forceinline__ int opaque_bid() { int t = blockIdx.x; asm volatile("" : "+s"(t)); return t; }
; template <bool OUT_F32, bool IN_BF16>
; __device__ __forceinline__ void phase_rmsnorm(const void* Xv, const float* gain, void* out) {
;     const float* X = (const float*)Xv; const bf16_t* Xb = (const bf16_t*)Xv;
;     const int tid = opaque_tid(), lane = tid & 63, wave = tid >> 6; const int bid = opaque_bid();
;     const int gw = bid * NWAVES + wave, NGW = gridDim.x * NWAVES;
;     f32x4 g[4][2];
; #pragma unroll
;     for (int j = 0; j < 4; ++j) { g[j][0] = *(const f32x4*)(gain + 8 * lane + 512 * j); g[j][1] = *(const f32x4*)(gain + 8 * lane + 512 * j + 4); }
;     constexpr int RPT = 4;
;     for (int m0 = gw; m0 < NTOK; m0 += RPT * NGW) {
;         f32x4 v[RPT][4][2]; u32x4 t[RPT][4];
; #pragma unroll
;         for (int r = 0; r < RPT; ++r) { const int mr = m0 + r * NGW, mc = mr < NTOK ? mr : m0;
; #pragma unroll
;             for (int j = 0; j < 4; ++j) { if (IN_BF16) t[r][j] = *(const u32x4*)(Xb + (size_t)mc * DM + 8 * lane + 512 * j);
;                 else { v[r][j][0] = *(const f32x4*)(X + (size_t)mc * DM + 8 * lane + 512 * j); v[r][j][1] = *(const f32x4*)(X + (size_t)mc * DM + 8 * lane + 512 * j + 4); } } }
;         float rs[RPT];
; #pragma unroll
;         for (int r = 0; r < RPT; ++r) { float sq = 0.f;
; #pragma unroll
;             for (int j = 0; j < 4; ++j) { if (IN_BF16) { const u32x4 q = t[r][j]; v[r][j][0] = (f32x4){bflo(q.x), bfhi(q.x), bflo(q.y), bfhi(q.y)}; v[r][j][1] = (f32x4){bflo(q.z), bfhi(q.z), bflo(q.w), bfhi(q.w)}; }
; #pragma unroll
;                 for (int h = 0; h < 2; ++h) { const f32x4 a = v[r][j][h]; sq += (a.x * a.x + a.y * a.y) + (a.z * a.z + a.w * a.w); } }
;             rs[r] = 1.0f / sqrtf(wave_sum(sq) * (1.0f / DM) + EPS); }
.Lln_begin:
	s_mov_b64 s[100:101], vcc
	s_and_b32 s0, s90, 7
	s_cmp_eq_u32 s0, 5
	s_cbranch_scc1 .Lln_k4
	s_cmp_lg_u32 s0, 0
	s_cbranch_scc1 .Lln_end
	s_cmp_eq_u32 s90, 32
	s_cbranch_scc1 .Lln_end
	s_lshr_b32 s1, s90, 3
	s_lshl_b32 s13, s1, 13
	s_lshl_b32 s1, s1, 1
	s_add_i32 s1, s1, -1
	s_mov_b32 s0, 0
	s_branch .Lln_go
.Lln_k4:
	s_add_i32 s1, s90, -5
	s_lshr_b32 s1, s1, 3
	s_lshl_b32 s13, s1, 13
	s_lshl_b32 s1, s1, 1
	s_mov_b32 s0, 1
.Lln_go:
	v_readlane_b32 s38, v252, 2
	v_readlane_b32 s39, v252, 3
	s_nop 0
	s_sub_u32 s38, s38, 0x90
	s_subb_u32 s39, s39, 0
	s_load_dwordx4 s[56:59], s[38:39], 0x38
	s_waitcnt lgkmcnt(0)
	s_cmp_eq_u32 s0, 1
	s_cselect_b32 s56, s58, s56
	s_cselect_b32 s57, s59, s57
	s_add_u32 s56, s56, s13
	s_addc_u32 s57, s57, 0
	v_readfirstlane_b32 s58, v174
	v_readfirstlane_b32 s59, v175
	s_add_u32 s64, s88, 0x1b900000
	s_addc_u32 s65, s89, 0
	s_sub_u32 s58, s58, s64
	s_subb_u32 s59, s59, s65
	s_lshr_b32 s13, s58, 20
	s_bfe_u32 s0, s58, 0x30009
	s_lshl_b32 s58, s1, 18
	s_lshl_b32 s59, s13, 13
	s_add_i32 s58, s58, s59
	s_add_u32 s38, s88, 0x30280000
	s_addc_u32 s39, s89, 0
	s_add_u32 s38, s38, s58
	s_addc_u32 s39, s39, 0
	s_lshl_b32 s1, s1, 5
	s_add_i32 s1, s1, s13
	s_lshl_b32 s1, s1, 6
	s_add_u32 s58, s88, 0x40a84000
	s_addc_u32 s59, s89, 0
	s_add_u32 s58, s58, s1
	s_addc_u32 s59, s59, 0
	s_lshl_b32 s1, s0, 10
	s_add_u32 s56, s56, s1
	s_addc_u32 s57, s57, 0
	v_lshrrev_b32_e32 v109, 6, v185
	v_and_b32_e32 v110, 3, v109
	v_lshrrev_b32_e32 v109, 2, v109
	v_bfe_u32 v111, v185, 4, 2
	v_and_b32_e32 v112, 15, v185
	v_lshlrev_b32_e32 v110, 7, v110
	v_lshl_add_u32 v110, v111, 5, v110
	v_lshlrev_b32_e32 v109, 6, v109
	v_add_u32_e32 v109, v109, v112
	v_lshrrev_b32_e32 v120, 7, v110
	v_lshlrev_b32_e32 v120, 2, v120
	v_lshl_add_u32 v108, v109, 4, v120
	v_add_u32_e32 v108, 0x20000, v108
	v_lshlrev_b32_e32 v111, 4, v185
	v_add_u32_e32 v111, 0x20000, v111
	v_and_b32_e32 v122, 63, v185
	v_xor_b32_e32 v123, 16, v122
	v_lshlrev_b32_e32 v123, 2, v123
	v_xor_b32_e32 v122, 32, v122
	v_lshlrev_b32_e32 v122, 2, v122
	v_lshlrev_b32_e32 v112, 5, v185
	s_lshl_b32 s1, s0, 2
	v_add_u32_e32 v113, s1, v112
	v_mov_b32_e32 v114, 1
	s_waitcnt vmcnt(0)
	s_mov_b32 s64, 0x10000
	s_mov_b32 s65, 0
	v_mov_b32_e32 v104, v174
	v_mov_b32_e32 v105, v175
	global_load_dwordx4 v[0:3], v[104:105], off
	global_load_dwordx4 v[4:7], v[104:105], off offset:256
	v_lshl_add_u64 v[104:105], v[104:105], 0, s[64:65]
	global_load_dwordx4 v[8:11], v[104:105], off
	global_load_dwordx4 v[12:15], v[104:105], off offset:256
	v_lshl_add_u64 v[104:105], v[104:105], 0, s[64:65]
	global_load_dwordx4 v[16:19], v[104:105], off
	global_load_dwordx4 v[20:23], v[104:105], off offset:256
	v_lshl_add_u64 v[104:105], v[104:105], 0, s[64:65]
	global_load_dwordx4 v[24:27], v[104:105], off
	global_load_dwordx4 v[28:31], v[104:105], off offset:256
	s_mov_b32 s64, 0x50000
	v_lshl_add_u64 v[104:105], v[104:105], 0, s[64:65]
	s_mov_b32 s64, 0x10000
	global_load_dwordx4 v[32:35], v[104:105], off
	global_load_dwordx4 v[36:39], v[104:105], off offset:256
	v_lshl_add_u64 v[104:105], v[104:105], 0, s[64:65]
	global_load_dwordx4 v[40:43], v[104:105], off
	global_load_dwordx4 v[44:47], v[104:105], off offset:256
	v_lshl_add_u64 v[104:105], v[104:105], 0, s[64:65]
	global_load_dwordx4 v[48:51], v[104:105], off
	global_load_dwordx4 v[52:55], v[104:105], off offset:256
	v_lshl_add_u64 v[104:105], v[104:105], 0, s[64:65]
	global_load_dwordx4 v[56:59], v[104:105], off
	global_load_dwordx4 v[60:63], v[104:105], off offset:256
	global_load_dwordx4 v[80:83], v110, s[56:57]
	global_load_dwordx4 v[84:87], v110, s[56:57] offset:16
	global_load_dwordx4 v[88:91], v110, s[56:57] offset:512
	global_load_dwordx4 v[92:95], v110, s[56:57] offset:528
	v_mov_b32_e32 v72, 0
	v_mov_b32_e32 v73, 0
	v_mov_b32_e32 v74, 0
	v_mov_b32_e32 v75, 0
	v_mov_b32_e32 v76, 0
	v_mov_b32_e32 v77, 0
	v_mov_b32_e32 v78, 0
	v_mov_b32_e32 v79, 0
	s_waitcnt vmcnt(19)
	v_lshlrev_b32_e32 v64, 16, v0
	v_and_b32_e32 v65, 0xffff0000, v0
	v_lshlrev_b32_e32 v66, 16, v1
	v_and_b32_e32 v67, 0xffff0000, v1
	v_lshlrev_b32_e32 v68, 16, v2
	v_and_b32_e32 v69, 0xffff0000, v2
	v_lshlrev_b32_e32 v70, 16, v3
	v_and_b32_e32 v71, 0xffff0000, v3
	v_fmac_f32_e32 v72, v64, v64
	v_fmac_f32_e32 v72, v65, v65
	v_fmac_f32_e32 v72, v66, v66
	v_fmac_f32_e32 v72, v67, v67
	v_fmac_f32_e32 v72, v68, v68
	v_fmac_f32_e32 v72, v69, v69
	v_fmac_f32_e32 v72, v70, v70
	v_fmac_f32_e32 v72, v71, v71
	s_waitcnt vmcnt(18)
	v_lshlrev_b32_e32 v64, 16, v4
	v_and_b32_e32 v65, 0xffff0000, v4
	v_lshlrev_b32_e32 v66, 16, v5
	v_and_b32_e32 v67, 0xffff0000, v5
	v_lshlrev_b32_e32 v68, 16, v6
	v_and_b32_e32 v69, 0xffff0000, v6
	v_lshlrev_b32_e32 v70, 16, v7
	v_and_b32_e32 v71, 0xffff0000, v7
	v_fmac_f32_e32 v72, v64, v64
	v_fmac_f32_e32 v72, v65, v65
	v_fmac_f32_e32 v72, v66, v66
	v_fmac_f32_e32 v72, v67, v67
	v_fmac_f32_e32 v72, v68, v68
	v_fmac_f32_e32 v72, v69, v69
	v_fmac_f32_e32 v72, v70, v70
	v_fmac_f32_e32 v72, v71, v71
	s_waitcnt vmcnt(17)
	v_lshlrev_b32_e32 v64, 16, v8
	v_and_b32_e32 v65, 0xffff0000, v8
	v_lshlrev_b32_e32 v66, 16, v9
	v_and_b32_e32 v67, 0xffff0000, v9
	v_lshlrev_b32_e32 v68, 16, v10
	v_and_b32_e32 v69, 0xffff0000, v10
	v_lshlrev_b32_e32 v70, 16, v11
	v_and_b32_e32 v71, 0xffff0000, v11
	v_fmac_f32_e32 v73, v64, v64
	v_fmac_f32_e32 v73, v65, v65
	v_fmac_f32_e32 v73, v66, v66
	v_fmac_f32_e32 v73, v67, v67
	v_fmac_f32_e32 v73, v68, v68
	v_fmac_f32_e32 v73, v69, v69
	v_fmac_f32_e32 v73, v70, v70
	v_fmac_f32_e32 v73, v71, v71
	s_waitcnt vmcnt(16)
; __device__ __forceinline__ float bflo(unsigned w) { return __uint_as_float(w << 16); }
; __device__ __forceinline__ float bfhi(unsigned w) { return __uint_as_float(w & 0xffff0000u); }
; template <bool OUT_F32, bool IN_BF16>
; __device__ __forceinline__ void phase_rmsnorm(const void* Xv, const float* gain, void* out) {
;     ...
;         float rs[RPT];
; #pragma unroll
;         for (int r = 0; r < RPT; ++r) { float sq = 0.f;
; #pragma unroll
;             for (int j = 0; j < 4; ++j) { if (IN_BF16) { const u32x4 q = t[r][j]; v[r][j][0] = (f32x4){bflo(q.x), bfhi(q.x), bflo(q.y), bfhi(q.y)}; v[r][j][1] = (f32x4){bflo(q.z), bfhi(q.z), bflo(q.w), bfhi(q.w)}; }
; #pragma unroll
;                 for (int h = 0; h < 2; ++h) { const f32x4 a = v[r][j][h]; sq += (a.x * a.x + a.y * a.y) + (a.z * a.z + a.w * a.w); } }
;             rs[r] = 1.0f / sqrtf(wave_sum(sq) * (1.0f / DM) + EPS); }
	v_lshlrev_b32_e32 v64, 16, v12
	v_and_b32_e32 v65, 0xffff0000, v12
	v_lshlrev_b32_e32 v66, 16, v13
	v_and_b32_e32 v67, 0xffff0000, v13
	v_lshlrev_b32_e32 v68, 16, v14
	v_and_b32_e32 v69, 0xffff0000, v14
	v_lshlrev_b32_e32 v70, 16, v15
	v_and_b32_e32 v71, 0xffff0000, v15
	v_fmac_f32_e32 v73, v64, v64
	v_fmac_f32_e32 v73, v65, v65
	v_fmac_f32_e32 v73, v66, v66
	v_fmac_f32_e32 v73, v67, v67
	v_fmac_f32_e32 v73, v68, v68
	v_fmac_f32_e32 v73, v69, v69
	v_fmac_f32_e32 v73, v70, v70
	v_fmac_f32_e32 v73, v71, v71
	s_waitcnt vmcnt(15)
	v_lshlrev_b32_e32 v64, 16, v16
	v_and_b32_e32 v65, 0xffff0000, v16
	v_lshlrev_b32_e32 v66, 16, v17
	v_and_b32_e32 v67, 0xffff0000, v17
	v_lshlrev_b32_e32 v68, 16, v18
	v_and_b32_e32 v69, 0xffff0000, v18
	v_lshlrev_b32_e32 v70, 16, v19
	v_and_b32_e32 v71, 0xffff0000, v19
	v_fmac_f32_e32 v74, v64, v64
	v_fmac_f32_e32 v74, v65, v65
	v_fmac_f32_e32 v74, v66, v66
	v_fmac_f32_e32 v74, v67, v67
	v_fmac_f32_e32 v74, v68, v68
	v_fmac_f32_e32 v74, v69, v69
	v_fmac_f32_e32 v74, v70, v70
	v_fmac_f32_e32 v74, v71, v71
	s_waitcnt vmcnt(14)
	v_lshlrev_b32_e32 v64, 16, v20
	v_and_b32_e32 v65, 0xffff0000, v20
	v_lshlrev_b32_e32 v66, 16, v21
	v_and_b32_e32 v67, 0xffff0000, v21
	v_lshlrev_b32_e32 v68, 16, v22
	v_and_b32_e32 v69, 0xffff0000, v22
	v_lshlrev_b32_e32 v70, 16, v23
	v_and_b32_e32 v71, 0xffff0000, v23
	v_fmac_f32_e32 v74, v64, v64
	v_fmac_f32_e32 v74, v65, v65
	v_fmac_f32_e32 v74, v66, v66
	v_fmac_f32_e32 v74, v67, v67
	v_fmac_f32_e32 v74, v68, v68
	v_fmac_f32_e32 v74, v69, v69
	v_fmac_f32_e32 v74, v70, v70
	v_fmac_f32_e32 v74, v71, v71
	s_waitcnt vmcnt(13)
	v_lshlrev_b32_e32 v64, 16, v24
	v_and_b32_e32 v65, 0xffff0000, v24
	v_lshlrev_b32_e32 v66, 16, v25
	v_and_b32_e32 v67, 0xffff0000, v25
	v_lshlrev_b32_e32 v68, 16, v26
	v_and_b32_e32 v69, 0xffff0000, v26
	v_lshlrev_b32_e32 v70, 16, v27
	v_and_b32_e32 v71, 0xffff0000, v27
	v_fmac_f32_e32 v75, v64, v64
	v_fmac_f32_e32 v75, v65, v65
	v_fmac_f32_e32 v75, v66, v66
	v_fmac_f32_e32 v75, v67, v67
	v_fmac_f32_e32 v75, v68, v68
	v_fmac_f32_e32 v75, v69, v69
	v_fmac_f32_e32 v75, v70, v70
	v_fmac_f32_e32 v75, v71, v71
	s_waitcnt vmcnt(12)
	v_lshlrev_b32_e32 v64, 16, v28
	v_and_b32_e32 v65, 0xffff0000, v28
	v_lshlrev_b32_e32 v66, 16, v29
	v_and_b32_e32 v67, 0xffff0000, v29
	v_lshlrev_b32_e32 v68, 16, v30
	v_and_b32_e32 v69, 0xffff0000, v30
	v_lshlrev_b32_e32 v70, 16, v31
	v_and_b32_e32 v71, 0xffff0000, v31
	v_fmac_f32_e32 v75, v64, v64
	v_fmac_f32_e32 v75, v65, v65
	v_fmac_f32_e32 v75, v66, v66
	v_fmac_f32_e32 v75, v67, v67
	v_fmac_f32_e32 v75, v68, v68
	v_fmac_f32_e32 v75, v69, v69
	v_fmac_f32_e32 v75, v70, v70
	v_fmac_f32_e32 v75, v71, v71
	s_waitcnt vmcnt(11)
	v_lshlrev_b32_e32 v64, 16, v32
	v_and_b32_e32 v65, 0xffff0000, v32
	v_lshlrev_b32_e32 v66, 16, v33
	v_and_b32_e32 v67, 0xffff0000, v33
	v_lshlrev_b32_e32 v68, 16, v34
	v_and_b32_e32 v69, 0xffff0000, v34
	v_lshlrev_b32_e32 v70, 16, v35
	v_and_b32_e32 v71, 0xffff0000, v35
	v_fmac_f32_e32 v76, v64, v64
	v_fmac_f32_e32 v76, v65, v65
	v_fmac_f32_e32 v76, v66, v66
	v_fmac_f32_e32 v76, v67, v67
	v_fmac_f32_e32 v76, v68, v68
	v_fmac_f32_e32 v76, v69, v69
	v_fmac_f32_e32 v76, v70, v70
	v_fmac_f32_e32 v76, v71, v71
	s_waitcnt vmcnt(10)
	v_lshlrev_b32_e32 v64, 16, v36
	v_and_b32_e32 v65, 0xffff0000, v36
	v_lshlrev_b32_e32 v66, 16, v37
	v_and_b32_e32 v67, 0xffff0000, v37
	v_lshlrev_b32_e32 v68, 16, v38
	v_and_b32_e32 v69, 0xffff0000, v38
	v_lshlrev_b32_e32 v70, 16, v39
	v_and_b32_e32 v71, 0xffff0000, v39
	v_fmac_f32_e32 v76, v64, v64
	v_fmac_f32_e32 v76, v65, v65
	v_fmac_f32_e32 v76, v66, v66
	v_fmac_f32_e32 v76, v67, v67
	v_fmac_f32_e32 v76, v68, v68
	v_fmac_f32_e32 v76, v69, v69
	v_fmac_f32_e32 v76, v70, v70
	v_fmac_f32_e32 v76, v71, v71
	s_waitcnt vmcnt(9)
	v_lshlrev_b32_e32 v64, 16, v40
	v_and_b32_e32 v65, 0xffff0000, v40
	v_lshlrev_b32_e32 v66, 16, v41
	v_and_b32_e32 v67, 0xffff0000, v41
	v_lshlrev_b32_e32 v68, 16, v42
	v_and_b32_e32 v69, 0xffff0000, v42
	v_lshlrev_b32_e32 v70, 16, v43
	v_and_b32_e32 v71, 0xffff0000, v43
	v_fmac_f32_e32 v77, v64, v64
	v_fmac_f32_e32 v77, v65, v65
	v_fmac_f32_e32 v77, v66, v66
	v_fmac_f32_e32 v77, v67, v67
	v_fmac_f32_e32 v77, v68, v68
	v_fmac_f32_e32 v77, v69, v69
	v_fmac_f32_e32 v77, v70, v70
	v_fmac_f32_e32 v77, v71, v71
	s_waitcnt vmcnt(8)
	v_lshlrev_b32_e32 v64, 16, v44
	v_and_b32_e32 v65, 0xffff0000, v44
	v_lshlrev_b32_e32 v66, 16, v45
	v_and_b32_e32 v67, 0xffff0000, v45
	v_lshlrev_b32_e32 v68, 16, v46
	v_and_b32_e32 v69, 0xffff0000, v46
	v_lshlrev_b32_e32 v70, 16, v47
	v_and_b32_e32 v71, 0xffff0000, v47
	v_fmac_f32_e32 v77, v64, v64
	v_fmac_f32_e32 v77, v65, v65
	v_fmac_f32_e32 v77, v66, v66
	v_fmac_f32_e32 v77, v67, v67
	v_fmac_f32_e32 v77, v68, v68
	v_fmac_f32_e32 v77, v69, v69
	v_fmac_f32_e32 v77, v70, v70
	v_fmac_f32_e32 v77, v71, v71
	s_waitcnt vmcnt(7)
	v_lshlrev_b32_e32 v64, 16, v48
	v_and_b32_e32 v65, 0xffff0000, v48
	v_lshlrev_b32_e32 v66, 16, v49
	v_and_b32_e32 v67, 0xffff0000, v49
	v_lshlrev_b32_e32 v68, 16, v50
	v_and_b32_e32 v69, 0xffff0000, v50
	v_lshlrev_b32_e32 v70, 16, v51
	v_and_b32_e32 v71, 0xffff0000, v51
	v_fmac_f32_e32 v78, v64, v64
	v_fmac_f32_e32 v78, v65, v65
	v_fmac_f32_e32 v78, v66, v66
	v_fmac_f32_e32 v78, v67, v67
	v_fmac_f32_e32 v78, v68, v68
	v_fmac_f32_e32 v78, v69, v69
	v_fmac_f32_e32 v78, v70, v70
	v_fmac_f32_e32 v78, v71, v71
	s_waitcnt vmcnt(6)
	v_lshlrev_b32_e32 v64, 16, v52
	v_and_b32_e32 v65, 0xffff0000, v52
	v_lshlrev_b32_e32 v66, 16, v53
	v_and_b32_e32 v67, 0xffff0000, v53
	v_lshlrev_b32_e32 v68, 16, v54
	v_and_b32_e32 v69, 0xffff0000, v54
	v_lshlrev_b32_e32 v70, 16, v55
	v_and_b32_e32 v71, 0xffff0000, v55
	v_fmac_f32_e32 v78, v64, v64
	v_fmac_f32_e32 v78, v65, v65
	v_fmac_f32_e32 v78, v66, v66
	v_fmac_f32_e32 v78, v67, v67
	v_fmac_f32_e32 v78, v68, v68
	v_fmac_f32_e32 v78, v69, v69
	v_fmac_f32_e32 v78, v70, v70
	v_fmac_f32_e32 v78, v71, v71
	s_waitcnt vmcnt(5)
; __device__ __forceinline__ float bflo(unsigned w) { return __uint_as_float(w << 16); }
; __device__ __forceinline__ float bfhi(unsigned w) { return __uint_as_float(w & 0xffff0000u); }
; template <bool OUT_F32, bool IN_BF16>
; __device__ __forceinline__ void phase_rmsnorm(const void* Xv, const float* gain, void* out) {
;     ...
;         for (int r = 0; r < RPT; ++r) { float sq = 0.f;
; #pragma unroll
;             for (int j = 0; j < 4; ++j) { if (IN_BF16) { const u32x4 q = t[r][j]; v[r][j][0] = (f32x4){bflo(q.x), bfhi(q.x), bflo(q.y), bfhi(q.y)}; v[r][j][1] = (f32x4){bflo(q.z), bfhi(q.z), bflo(q.w), bfhi(q.w)}; }
; #pragma unroll
;                 for (int h = 0; h < 2; ++h) { const f32x4 a = v[r][j][h]; sq += (a.x * a.x + a.y * a.y) + (a.z * a.z + a.w * a.w); } }
;             rs[r] = 1.0f / sqrtf(wave_sum(sq) * (1.0f / DM) + EPS); }
	v_lshlrev_b32_e32 v64, 16, v56
	v_and_b32_e32 v65, 0xffff0000, v56
	v_lshlrev_b32_e32 v66, 16, v57
	v_and_b32_e32 v67, 0xffff0000, v57
	v_lshlrev_b32_e32 v68, 16, v58
	v_and_b32_e32 v69, 0xffff0000, v58
	v_lshlrev_b32_e32 v70, 16, v59
	v_and_b32_e32 v71, 0xffff0000, v59
	v_fmac_f32_e32 v79, v64, v64
	v_fmac_f32_e32 v79, v65, v65
	v_fmac_f32_e32 v79, v66, v66
	v_fmac_f32_e32 v79, v67, v67
	v_fmac_f32_e32 v79, v68, v68
	v_fmac_f32_e32 v79, v69, v69
	v_fmac_f32_e32 v79, v70, v70
	v_fmac_f32_e32 v79, v71, v71
	s_waitcnt vmcnt(4)
	v_lshlrev_b32_e32 v64, 16, v60
	v_and_b32_e32 v65, 0xffff0000, v60
	v_lshlrev_b32_e32 v66, 16, v61
	v_and_b32_e32 v67, 0xffff0000, v61
	v_lshlrev_b32_e32 v68, 16, v62
	v_and_b32_e32 v69, 0xffff0000, v62
	v_lshlrev_b32_e32 v70, 16, v63
	v_and_b32_e32 v71, 0xffff0000, v63
	v_fmac_f32_e32 v79, v64, v64
	v_fmac_f32_e32 v79, v65, v65
	v_fmac_f32_e32 v79, v66, v66
	v_fmac_f32_e32 v79, v67, v67
	v_fmac_f32_e32 v79, v68, v68
	v_fmac_f32_e32 v79, v69, v69
	v_fmac_f32_e32 v79, v70, v70
	v_fmac_f32_e32 v79, v71, v71
	ds_bpermute_b32 v64, v123, v72
	ds_bpermute_b32 v65, v123, v73
	ds_bpermute_b32 v66, v123, v74
	ds_bpermute_b32 v67, v123, v75
	ds_bpermute_b32 v68, v123, v76
	ds_bpermute_b32 v69, v123, v77
	ds_bpermute_b32 v70, v123, v78
	ds_bpermute_b32 v71, v123, v79
	s_waitcnt lgkmcnt(0)
	v_add_f32_e32 v72, v72, v64
	v_add_f32_e32 v73, v73, v65
	v_add_f32_e32 v74, v74, v66
	v_add_f32_e32 v75, v75, v67
	v_add_f32_e32 v76, v76, v68
	v_add_f32_e32 v77, v77, v69
	v_add_f32_e32 v78, v78, v70
	v_add_f32_e32 v79, v79, v71
	ds_bpermute_b32 v64, v122, v72
	ds_bpermute_b32 v65, v122, v73
	ds_bpermute_b32 v66, v122, v74
	ds_bpermute_b32 v67, v122, v75
	ds_bpermute_b32 v68, v122, v76
	ds_bpermute_b32 v69, v122, v77
	ds_bpermute_b32 v70, v122, v78
	ds_bpermute_b32 v71, v122, v79
	s_waitcnt lgkmcnt(0)
	v_add_f32_e32 v72, v72, v64
	v_add_f32_e32 v73, v73, v65
	v_add_f32_e32 v74, v74, v66
	v_add_f32_e32 v75, v75, v67
	v_add_f32_e32 v76, v76, v68
	v_add_f32_e32 v77, v77, v69
	v_add_f32_e32 v78, v78, v70
	v_add_f32_e32 v79, v79, v71
	v_and_b32_e32 v115, 48, v185
	v_cmp_eq_u32_e32 vcc, 0, v115
	s_and_saveexec_b64 s[64:65], vcc
	ds_write_b32 v108, v72 offset:0
	ds_write_b32 v108, v73 offset:256
	ds_write_b32 v108, v74 offset:512
	ds_write_b32 v108, v75 offset:768
	ds_write_b32 v108, v76 offset:2048
	ds_write_b32 v108, v77 offset:2304
	ds_write_b32 v108, v78 offset:2560
	ds_write_b32 v108, v79 offset:2816
	s_or_b64 exec, exec, s[64:65]
	s_waitcnt lgkmcnt(0)
	s_barrier
	v_cmp_gt_u32_e32 vcc, 0x100, v185
	s_and_saveexec_b64 s[64:65], vcc
	s_cbranch_execz .Lln_pub_done
	ds_read_b128 v[116:119], v111
	s_waitcnt lgkmcnt(0)
	v_add_f32_e32 v116, v116, v117
	v_add_f32_e32 v118, v118, v119
	v_add_f32_e32 v115, v116, v118
	global_store_dword v113, v115, s[38:39] sc0 sc1
	s_waitcnt vmcnt(0)
.Lln_pub_done:
	s_or_b64 exec, exec, s[64:65]
	s_barrier
	v_cmp_eq_u32_e32 vcc, 0, v185
	s_and_saveexec_b64 s[64:65], vcc
	s_cbranch_execz .Lln_wait_done
	global_atomic_add v183, v114, s[58:59]
	s_mov_b32 s1, 0
.Lln_spin:
	global_load_dword v115, v183, s[58:59] sc1
	s_waitcnt vmcnt(0)
	v_cmp_gt_u32_e32 vcc, 8, v115
	s_cbranch_vccz .Lln_spin_done
	s_sleep 1
	s_add_i32 s1, s1, 1
	s_cmp_lt_u32 s1, 0x4000
	s_cbranch_scc1 .Lln_spin
.Lln_spin_done:
	buffer_inv sc1
	s_waitcnt vmcnt(0)
.Lln_wait_done:
	s_or_b64 exec, exec, s[64:65]
	s_barrier
	v_cmp_gt_u32_e32 vcc, 0x100, v185
	s_and_saveexec_b64 s[64:65], vcc
	s_cbranch_execz .Lln_rs_done
	global_load_dwordx4 v[116:119], v112, s[38:39] sc1
	global_load_dwordx4 v[120:123], v112, s[38:39] offset:16 sc1
	s_waitcnt vmcnt(0)
	v_add_f32_e32 v116, v116, v117
	v_add_f32_e32 v118, v118, v119
	v_add_f32_e32 v120, v120, v121
	v_add_f32_e32 v122, v122, v123
	v_add_f32_e32 v116, v116, v118
	v_add_f32_e32 v120, v120, v122
	v_add_f32_e32 v116, v116, v120
	v_mov_b32_e32 v117, 0x358637bd
	v_fmac_f32_e32 v117, 0x3a000000, v116
	v_rsq_f32_e32 v117, v117
	v_lshlrev_b32_e32 v118, 2, v185
	v_add_u32_e32 v118, 0x21000, v118
	s_nop 0
	ds_write_b32 v118, v117
.Lln_rs_done:
	s_or_b64 exec, exec, s[64:65]
	s_waitcnt lgkmcnt(0)
	s_barrier
	v_lshlrev_b32_e32 v105, 2, v109
	v_add_u32_e32 v105, 0x21000, v105
	ds_read_b32 v96, v105 offset:0
	ds_read_b32 v97, v105 offset:64
	ds_read_b32 v98, v105 offset:128
	ds_read_b32 v99, v105 offset:192
	ds_read_b32 v100, v105 offset:512
	ds_read_b32 v101, v105 offset:576
	ds_read_b32 v102, v105 offset:640
	ds_read_b32 v103, v105 offset:704
	s_mov_b32 s64, 0x4000000
	s_mov_b32 s65, 0
	v_lshl_add_u64 v[106:107], v[174:175], 0, s[64:65]
	s_mov_b32 s64, 0x10000
	s_waitcnt lgkmcnt(0)
; __device__ __forceinline__ unsigned pk2(float lo, float hi) { const f32x2 v = {lo, hi}; const hwbf16x2 b = __builtin_convertvector(v, hwbf16x2); return __builtin_bit_cast(unsigned, b); }
; template <bool OUT_F32, bool IN_BF16>
; __device__ __forceinline__ void phase_rmsnorm(const void* Xv, const float* gain, void* out) {
;     ...
;         for (int r = 0; r < RPT; ++r) { const int m = m0 + r * NGW; if (m >= NTOK) continue;
; #pragma unroll
;             for (int j = 0; j < 4; ++j) { const f32x4 y0 = v[r][j][0] * rs[r] * g[j][0], y1 = v[r][j][1] * rs[r] * g[j][1];
;                 if (OUT_F32) { float* o = (float*)out + (size_t)m * DM + 8 * lane + 512 * j; *(f32x4*)o = y0; *(f32x4*)(o + 4) = y1; }
;                 else { u32x4 w; w.x = pk2(y0.x, y0.y); w.y = pk2(y0.z, y0.w); w.z = pk2(y1.x, y1.y); w.w = pk2(y1.z, y1.w); *(u32x4*)((bf16_t*)out + (size_t)m * DM + 8 * lane + 512 * j) = w; } } }
	v_lshlrev_b32_e32 v64, 16, v0
	v_and_b32_e32 v65, 0xffff0000, v0
	v_lshlrev_b32_e32 v66, 16, v1
	v_and_b32_e32 v67, 0xffff0000, v1
	v_lshlrev_b32_e32 v68, 16, v2
	v_and_b32_e32 v69, 0xffff0000, v2
	v_lshlrev_b32_e32 v70, 16, v3
	v_and_b32_e32 v71, 0xffff0000, v3
	v_mul_f32_e32 v64, v64, v96
	v_mul_f32_e32 v65, v65, v96
	v_mul_f32_e32 v66, v66, v96
	v_mul_f32_e32 v67, v67, v96
	v_mul_f32_e32 v68, v68, v96
	v_mul_f32_e32 v69, v69, v96
	v_mul_f32_e32 v70, v70, v96
	v_mul_f32_e32 v71, v71, v96
	v_pk_mul_f32 v[64:65], v[64:65], v[80:81]
	v_pk_mul_f32 v[66:67], v[66:67], v[82:83]
	v_pk_mul_f32 v[68:69], v[68:69], v[84:85]
	v_pk_mul_f32 v[70:71], v[70:71], v[86:87]
	v_cvt_pk_bf16_f32 v124, v64, v65
	v_cvt_pk_bf16_f32 v125, v66, v67
	v_cvt_pk_bf16_f32 v126, v68, v69
	v_cvt_pk_bf16_f32 v127, v70, v71
	global_store_dwordx4 v[106:107], v[124:127], off
	v_lshlrev_b32_e32 v64, 16, v4
	v_and_b32_e32 v65, 0xffff0000, v4
	v_lshlrev_b32_e32 v66, 16, v5
	v_and_b32_e32 v67, 0xffff0000, v5
	v_lshlrev_b32_e32 v68, 16, v6
	v_and_b32_e32 v69, 0xffff0000, v6
	v_lshlrev_b32_e32 v70, 16, v7
	v_and_b32_e32 v71, 0xffff0000, v7
	v_mul_f32_e32 v64, v64, v96
	v_mul_f32_e32 v65, v65, v96
	v_mul_f32_e32 v66, v66, v96
	v_mul_f32_e32 v67, v67, v96
	v_mul_f32_e32 v68, v68, v96
	v_mul_f32_e32 v69, v69, v96
	v_mul_f32_e32 v70, v70, v96
	v_mul_f32_e32 v71, v71, v96
	v_pk_mul_f32 v[64:65], v[64:65], v[88:89]
	v_pk_mul_f32 v[66:67], v[66:67], v[90:91]
	v_pk_mul_f32 v[68:69], v[68:69], v[92:93]
	v_pk_mul_f32 v[70:71], v[70:71], v[94:95]
	v_cvt_pk_bf16_f32 v124, v64, v65
	v_cvt_pk_bf16_f32 v125, v66, v67
	v_cvt_pk_bf16_f32 v126, v68, v69
	v_cvt_pk_bf16_f32 v127, v70, v71
	global_store_dwordx4 v[106:107], v[124:127], off offset:256
	v_lshl_add_u64 v[106:107], v[106:107], 0, s[64:65]
	v_lshlrev_b32_e32 v64, 16, v8
	v_and_b32_e32 v65, 0xffff0000, v8
	v_lshlrev_b32_e32 v66, 16, v9
	v_and_b32_e32 v67, 0xffff0000, v9
	v_lshlrev_b32_e32 v68, 16, v10
	v_and_b32_e32 v69, 0xffff0000, v10
	v_lshlrev_b32_e32 v70, 16, v11
	v_and_b32_e32 v71, 0xffff0000, v11
	v_mul_f32_e32 v64, v64, v97
	v_mul_f32_e32 v65, v65, v97
	v_mul_f32_e32 v66, v66, v97
	v_mul_f32_e32 v67, v67, v97
	v_mul_f32_e32 v68, v68, v97
	v_mul_f32_e32 v69, v69, v97
	v_mul_f32_e32 v70, v70, v97
	v_mul_f32_e32 v71, v71, v97
	v_pk_mul_f32 v[64:65], v[64:65], v[80:81]
	v_pk_mul_f32 v[66:67], v[66:67], v[82:83]
	v_pk_mul_f32 v[68:69], v[68:69], v[84:85]
	v_pk_mul_f32 v[70:71], v[70:71], v[86:87]
	v_cvt_pk_bf16_f32 v124, v64, v65
	v_cvt_pk_bf16_f32 v125, v66, v67
	v_cvt_pk_bf16_f32 v126, v68, v69
	v_cvt_pk_bf16_f32 v127, v70, v71
	global_store_dwordx4 v[106:107], v[124:127], off
	v_lshlrev_b32_e32 v64, 16, v12
	v_and_b32_e32 v65, 0xffff0000, v12
	v_lshlrev_b32_e32 v66, 16, v13
	v_and_b32_e32 v67, 0xffff0000, v13
	v_lshlrev_b32_e32 v68, 16, v14
	v_and_b32_e32 v69, 0xffff0000, v14
	v_lshlrev_b32_e32 v70, 16, v15
	v_and_b32_e32 v71, 0xffff0000, v15
	v_mul_f32_e32 v64, v64, v97
	v_mul_f32_e32 v65, v65, v97
	v_mul_f32_e32 v66, v66, v97
	v_mul_f32_e32 v67, v67, v97
	v_mul_f32_e32 v68, v68, v97
	v_mul_f32_e32 v69, v69, v97
	v_mul_f32_e32 v70, v70, v97
	v_mul_f32_e32 v71, v71, v97
	v_pk_mul_f32 v[64:65], v[64:65], v[88:89]
	v_pk_mul_f32 v[66:67], v[66:67], v[90:91]
	v_pk_mul_f32 v[68:69], v[68:69], v[92:93]
	v_pk_mul_f32 v[70:71], v[70:71], v[94:95]
	v_cvt_pk_bf16_f32 v124, v64, v65
	v_cvt_pk_bf16_f32 v125, v66, v67
	v_cvt_pk_bf16_f32 v126, v68, v69
	v_cvt_pk_bf16_f32 v127, v70, v71
	global_store_dwordx4 v[106:107], v[124:127], off offset:256
	v_lshl_add_u64 v[106:107], v[106:107], 0, s[64:65]
	v_lshlrev_b32_e32 v64, 16, v16
	v_and_b32_e32 v65, 0xffff0000, v16
	v_lshlrev_b32_e32 v66, 16, v17
	v_and_b32_e32 v67, 0xffff0000, v17
	v_lshlrev_b32_e32 v68, 16, v18
	v_and_b32_e32 v69, 0xffff0000, v18
	v_lshlrev_b32_e32 v70, 16, v19
	v_and_b32_e32 v71, 0xffff0000, v19
	v_mul_f32_e32 v64, v64, v98
	v_mul_f32_e32 v65, v65, v98
	v_mul_f32_e32 v66, v66, v98
	v_mul_f32_e32 v67, v67, v98
	v_mul_f32_e32 v68, v68, v98
	v_mul_f32_e32 v69, v69, v98
	v_mul_f32_e32 v70, v70, v98
	v_mul_f32_e32 v71, v71, v98
	v_pk_mul_f32 v[64:65], v[64:65], v[80:81]
	v_pk_mul_f32 v[66:67], v[66:67], v[82:83]
	v_pk_mul_f32 v[68:69], v[68:69], v[84:85]
	v_pk_mul_f32 v[70:71], v[70:71], v[86:87]
	v_cvt_pk_bf16_f32 v124, v64, v65
	v_cvt_pk_bf16_f32 v125, v66, v67
	v_cvt_pk_bf16_f32 v126, v68, v69
	v_cvt_pk_bf16_f32 v127, v70, v71
	global_store_dwordx4 v[106:107], v[124:127], off
	v_lshlrev_b32_e32 v64, 16, v20
	v_and_b32_e32 v65, 0xffff0000, v20
	v_lshlrev_b32_e32 v66, 16, v21
	v_and_b32_e32 v67, 0xffff0000, v21
	v_lshlrev_b32_e32 v68, 16, v22
	v_and_b32_e32 v69, 0xffff0000, v22
	v_lshlrev_b32_e32 v70, 16, v23
	v_and_b32_e32 v71, 0xffff0000, v23
	v_mul_f32_e32 v64, v64, v98
	v_mul_f32_e32 v65, v65, v98
	v_mul_f32_e32 v66, v66, v98
	v_mul_f32_e32 v67, v67, v98
	v_mul_f32_e32 v68, v68, v98
	v_mul_f32_e32 v69, v69, v98
	v_mul_f32_e32 v70, v70, v98
	v_mul_f32_e32 v71, v71, v98
	v_pk_mul_f32 v[64:65], v[64:65], v[88:89]
	v_pk_mul_f32 v[66:67], v[66:67], v[90:91]
	v_pk_mul_f32 v[68:69], v[68:69], v[92:93]
	v_pk_mul_f32 v[70:71], v[70:71], v[94:95]
	v_cvt_pk_bf16_f32 v124, v64, v65
	v_cvt_pk_bf16_f32 v125, v66, v67
	v_cvt_pk_bf16_f32 v126, v68, v69
	v_cvt_pk_bf16_f32 v127, v70, v71
	global_store_dwordx4 v[106:107], v[124:127], off offset:256
	v_lshl_add_u64 v[106:107], v[106:107], 0, s[64:65]
	v_lshlrev_b32_e32 v64, 16, v24
	v_and_b32_e32 v65, 0xffff0000, v24
	v_lshlrev_b32_e32 v66, 16, v25
	v_and_b32_e32 v67, 0xffff0000, v25
	v_lshlrev_b32_e32 v68, 16, v26
	v_and_b32_e32 v69, 0xffff0000, v26
	v_lshlrev_b32_e32 v70, 16, v27
	v_and_b32_e32 v71, 0xffff0000, v27
	v_mul_f32_e32 v64, v64, v99
; __device__ __forceinline__ unsigned pk2(float lo, float hi) { const f32x2 v = {lo, hi}; const hwbf16x2 b = __builtin_convertvector(v, hwbf16x2); return __builtin_bit_cast(unsigned, b); }
; template <bool OUT_F32, bool IN_BF16>
; __device__ __forceinline__ void phase_rmsnorm(const void* Xv, const float* gain, void* out) {
;     ...
;         for (int r = 0; r < RPT; ++r) { const int m = m0 + r * NGW; if (m >= NTOK) continue;
; #pragma unroll
;             for (int j = 0; j < 4; ++j) { const f32x4 y0 = v[r][j][0] * rs[r] * g[j][0], y1 = v[r][j][1] * rs[r] * g[j][1];
;                 if (OUT_F32) { float* o = (float*)out + (size_t)m * DM + 8 * lane + 512 * j; *(f32x4*)o = y0; *(f32x4*)(o + 4) = y1; }
;                 else { u32x4 w; w.x = pk2(y0.x, y0.y); w.y = pk2(y0.z, y0.w); w.z = pk2(y1.x, y1.y); w.w = pk2(y1.z, y1.w); *(u32x4*)((bf16_t*)out + (size_t)m * DM + 8 * lane + 512 * j) = w; } } }
	v_mul_f32_e32 v65, v65, v99
	v_mul_f32_e32 v66, v66, v99
	v_mul_f32_e32 v67, v67, v99
	v_mul_f32_e32 v68, v68, v99
	v_mul_f32_e32 v69, v69, v99
	v_mul_f32_e32 v70, v70, v99
	v_mul_f32_e32 v71, v71, v99
	v_pk_mul_f32 v[64:65], v[64:65], v[80:81]
	v_pk_mul_f32 v[66:67], v[66:67], v[82:83]
	v_pk_mul_f32 v[68:69], v[68:69], v[84:85]
	v_pk_mul_f32 v[70:71], v[70:71], v[86:87]
	v_cvt_pk_bf16_f32 v124, v64, v65
	v_cvt_pk_bf16_f32 v125, v66, v67
	v_cvt_pk_bf16_f32 v126, v68, v69
	v_cvt_pk_bf16_f32 v127, v70, v71
	global_store_dwordx4 v[106:107], v[124:127], off
	v_lshlrev_b32_e32 v64, 16, v28
	v_and_b32_e32 v65, 0xffff0000, v28
	v_lshlrev_b32_e32 v66, 16, v29
	v_and_b32_e32 v67, 0xffff0000, v29
	v_lshlrev_b32_e32 v68, 16, v30
	v_and_b32_e32 v69, 0xffff0000, v30
	v_lshlrev_b32_e32 v70, 16, v31
	v_and_b32_e32 v71, 0xffff0000, v31
	v_mul_f32_e32 v64, v64, v99
	v_mul_f32_e32 v65, v65, v99
	v_mul_f32_e32 v66, v66, v99
	v_mul_f32_e32 v67, v67, v99
	v_mul_f32_e32 v68, v68, v99
	v_mul_f32_e32 v69, v69, v99
	v_mul_f32_e32 v70, v70, v99
	v_mul_f32_e32 v71, v71, v99
	v_pk_mul_f32 v[64:65], v[64:65], v[88:89]
	v_pk_mul_f32 v[66:67], v[66:67], v[90:91]
	v_pk_mul_f32 v[68:69], v[68:69], v[92:93]
	v_pk_mul_f32 v[70:71], v[70:71], v[94:95]
	v_cvt_pk_bf16_f32 v124, v64, v65
	v_cvt_pk_bf16_f32 v125, v66, v67
	v_cvt_pk_bf16_f32 v126, v68, v69
	v_cvt_pk_bf16_f32 v127, v70, v71
	global_store_dwordx4 v[106:107], v[124:127], off offset:256
	s_mov_b32 s64, 0x50000
	v_lshl_add_u64 v[106:107], v[106:107], 0, s[64:65]
	s_mov_b32 s64, 0x10000
	v_lshlrev_b32_e32 v64, 16, v32
	v_and_b32_e32 v65, 0xffff0000, v32
	v_lshlrev_b32_e32 v66, 16, v33
	v_and_b32_e32 v67, 0xffff0000, v33
	v_lshlrev_b32_e32 v68, 16, v34
	v_and_b32_e32 v69, 0xffff0000, v34
	v_lshlrev_b32_e32 v70, 16, v35
	v_and_b32_e32 v71, 0xffff0000, v35
	v_mul_f32_e32 v64, v64, v100
	v_mul_f32_e32 v65, v65, v100
	v_mul_f32_e32 v66, v66, v100
	v_mul_f32_e32 v67, v67, v100
	v_mul_f32_e32 v68, v68, v100
	v_mul_f32_e32 v69, v69, v100
	v_mul_f32_e32 v70, v70, v100
	v_mul_f32_e32 v71, v71, v100
	v_pk_mul_f32 v[64:65], v[64:65], v[80:81]
	v_pk_mul_f32 v[66:67], v[66:67], v[82:83]
	v_pk_mul_f32 v[68:69], v[68:69], v[84:85]
	v_pk_mul_f32 v[70:71], v[70:71], v[86:87]
	v_cvt_pk_bf16_f32 v124, v64, v65
	v_cvt_pk_bf16_f32 v125, v66, v67
	v_cvt_pk_bf16_f32 v126, v68, v69
	v_cvt_pk_bf16_f32 v127, v70, v71
	global_store_dwordx4 v[106:107], v[124:127], off
	v_lshlrev_b32_e32 v64, 16, v36
	v_and_b32_e32 v65, 0xffff0000, v36
	v_lshlrev_b32_e32 v66, 16, v37
	v_and_b32_e32 v67, 0xffff0000, v37
	v_lshlrev_b32_e32 v68, 16, v38
	v_and_b32_e32 v69, 0xffff0000, v38
	v_lshlrev_b32_e32 v70, 16, v39
	v_and_b32_e32 v71, 0xffff0000, v39
	v_mul_f32_e32 v64, v64, v100
	v_mul_f32_e32 v65, v65, v100
	v_mul_f32_e32 v66, v66, v100
	v_mul_f32_e32 v67, v67, v100
	v_mul_f32_e32 v68, v68, v100
	v_mul_f32_e32 v69, v69, v100
	v_mul_f32_e32 v70, v70, v100
	v_mul_f32_e32 v71, v71, v100
	v_pk_mul_f32 v[64:65], v[64:65], v[88:89]
	v_pk_mul_f32 v[66:67], v[66:67], v[90:91]
	v_pk_mul_f32 v[68:69], v[68:69], v[92:93]
	v_pk_mul_f32 v[70:71], v[70:71], v[94:95]
	v_cvt_pk_bf16_f32 v124, v64, v65
	v_cvt_pk_bf16_f32 v125, v66, v67
	v_cvt_pk_bf16_f32 v126, v68, v69
	v_cvt_pk_bf16_f32 v127, v70, v71
	global_store_dwordx4 v[106:107], v[124:127], off offset:256
	v_lshl_add_u64 v[106:107], v[106:107], 0, s[64:65]
	v_lshlrev_b32_e32 v64, 16, v40
	v_and_b32_e32 v65, 0xffff0000, v40
	v_lshlrev_b32_e32 v66, 16, v41
	v_and_b32_e32 v67, 0xffff0000, v41
	v_lshlrev_b32_e32 v68, 16, v42
	v_and_b32_e32 v69, 0xffff0000, v42
	v_lshlrev_b32_e32 v70, 16, v43
	v_and_b32_e32 v71, 0xffff0000, v43
	v_mul_f32_e32 v64, v64, v101
	v_mul_f32_e32 v65, v65, v101
	v_mul_f32_e32 v66, v66, v101
	v_mul_f32_e32 v67, v67, v101
	v_mul_f32_e32 v68, v68, v101
	v_mul_f32_e32 v69, v69, v101
	v_mul_f32_e32 v70, v70, v101
	v_mul_f32_e32 v71, v71, v101
	v_pk_mul_f32 v[64:65], v[64:65], v[80:81]
	v_pk_mul_f32 v[66:67], v[66:67], v[82:83]
	v_pk_mul_f32 v[68:69], v[68:69], v[84:85]
	v_pk_mul_f32 v[70:71], v[70:71], v[86:87]
	v_cvt_pk_bf16_f32 v124, v64, v65
	v_cvt_pk_bf16_f32 v125, v66, v67
	v_cvt_pk_bf16_f32 v126, v68, v69
	v_cvt_pk_bf16_f32 v127, v70, v71
	global_store_dwordx4 v[106:107], v[124:127], off
	v_lshlrev_b32_e32 v64, 16, v44
	v_and_b32_e32 v65, 0xffff0000, v44
	v_lshlrev_b32_e32 v66, 16, v45
	v_and_b32_e32 v67, 0xffff0000, v45
	v_lshlrev_b32_e32 v68, 16, v46
	v_and_b32_e32 v69, 0xffff0000, v46
	v_lshlrev_b32_e32 v70, 16, v47
	v_and_b32_e32 v71, 0xffff0000, v47
	v_mul_f32_e32 v64, v64, v101
	v_mul_f32_e32 v65, v65, v101
; __device__ __forceinline__ unsigned pk2(float lo, float hi) { const f32x2 v = {lo, hi}; const hwbf16x2 b = __builtin_convertvector(v, hwbf16x2); return __builtin_bit_cast(unsigned, b); }
; template <bool OUT_F32, bool IN_BF16>
; __device__ __forceinline__ void phase_rmsnorm(const void* Xv, const float* gain, void* out) {
;     ...
;         for (int r = 0; r < RPT; ++r) { const int m = m0 + r * NGW; if (m >= NTOK) continue;
; #pragma unroll
;             for (int j = 0; j < 4; ++j) { const f32x4 y0 = v[r][j][0] * rs[r] * g[j][0], y1 = v[r][j][1] * rs[r] * g[j][1];
;                 if (OUT_F32) { float* o = (float*)out + (size_t)m * DM + 8 * lane + 512 * j; *(f32x4*)o = y0; *(f32x4*)(o + 4) = y1; }
;                 else { u32x4 w; w.x = pk2(y0.x, y0.y); w.y = pk2(y0.z, y0.w); w.z = pk2(y1.x, y1.y); w.w = pk2(y1.z, y1.w); *(u32x4*)((bf16_t*)out + (size_t)m * DM + 8 * lane + 512 * j) = w; } } }
; __global__ void __launch_bounds__(NTHREADS) fwd_megakernel(Params p) {
;     ...
;     for (int ph = p.ph_lo; ph < p.ph_hi; ++ph) {
	v_mul_f32_e32 v66, v66, v101
	v_mul_f32_e32 v67, v67, v101
	v_mul_f32_e32 v68, v68, v101
	v_mul_f32_e32 v69, v69, v101
	v_mul_f32_e32 v70, v70, v101
	v_mul_f32_e32 v71, v71, v101
	v_pk_mul_f32 v[64:65], v[64:65], v[88:89]
	v_pk_mul_f32 v[66:67], v[66:67], v[90:91]
	v_pk_mul_f32 v[68:69], v[68:69], v[92:93]
	v_pk_mul_f32 v[70:71], v[70:71], v[94:95]
	v_cvt_pk_bf16_f32 v124, v64, v65
	v_cvt_pk_bf16_f32 v125, v66, v67
	v_cvt_pk_bf16_f32 v126, v68, v69
	v_cvt_pk_bf16_f32 v127, v70, v71
	global_store_dwordx4 v[106:107], v[124:127], off offset:256
	v_lshl_add_u64 v[106:107], v[106:107], 0, s[64:65]
	v_lshlrev_b32_e32 v64, 16, v48
	v_and_b32_e32 v65, 0xffff0000, v48
	v_lshlrev_b32_e32 v66, 16, v49
	v_and_b32_e32 v67, 0xffff0000, v49
	v_lshlrev_b32_e32 v68, 16, v50
	v_and_b32_e32 v69, 0xffff0000, v50
	v_lshlrev_b32_e32 v70, 16, v51
	v_and_b32_e32 v71, 0xffff0000, v51
	v_mul_f32_e32 v64, v64, v102
	v_mul_f32_e32 v65, v65, v102
	v_mul_f32_e32 v66, v66, v102
	v_mul_f32_e32 v67, v67, v102
	v_mul_f32_e32 v68, v68, v102
	v_mul_f32_e32 v69, v69, v102
	v_mul_f32_e32 v70, v70, v102
	v_mul_f32_e32 v71, v71, v102
	v_pk_mul_f32 v[64:65], v[64:65], v[80:81]
	v_pk_mul_f32 v[66:67], v[66:67], v[82:83]
	v_pk_mul_f32 v[68:69], v[68:69], v[84:85]
	v_pk_mul_f32 v[70:71], v[70:71], v[86:87]
	v_cvt_pk_bf16_f32 v124, v64, v65
	v_cvt_pk_bf16_f32 v125, v66, v67
	v_cvt_pk_bf16_f32 v126, v68, v69
	v_cvt_pk_bf16_f32 v127, v70, v71
	global_store_dwordx4 v[106:107], v[124:127], off
	v_lshlrev_b32_e32 v64, 16, v52
	v_and_b32_e32 v65, 0xffff0000, v52
	v_lshlrev_b32_e32 v66, 16, v53
	v_and_b32_e32 v67, 0xffff0000, v53
	v_lshlrev_b32_e32 v68, 16, v54
	v_and_b32_e32 v69, 0xffff0000, v54
	v_lshlrev_b32_e32 v70, 16, v55
	v_and_b32_e32 v71, 0xffff0000, v55
	v_mul_f32_e32 v64, v64, v102
	v_mul_f32_e32 v65, v65, v102
	v_mul_f32_e32 v66, v66, v102
	v_mul_f32_e32 v67, v67, v102
	v_mul_f32_e32 v68, v68, v102
	v_mul_f32_e32 v69, v69, v102
	v_mul_f32_e32 v70, v70, v102
	v_mul_f32_e32 v71, v71, v102
	v_pk_mul_f32 v[64:65], v[64:65], v[88:89]
	v_pk_mul_f32 v[66:67], v[66:67], v[90:91]
	v_pk_mul_f32 v[68:69], v[68:69], v[92:93]
	v_pk_mul_f32 v[70:71], v[70:71], v[94:95]
	v_cvt_pk_bf16_f32 v124, v64, v65
	v_cvt_pk_bf16_f32 v125, v66, v67
	v_cvt_pk_bf16_f32 v126, v68, v69
	v_cvt_pk_bf16_f32 v127, v70, v71
	global_store_dwordx4 v[106:107], v[124:127], off offset:256
	v_lshl_add_u64 v[106:107], v[106:107], 0, s[64:65]
	v_lshlrev_b32_e32 v64, 16, v56
	v_and_b32_e32 v65, 0xffff0000, v56
	v_lshlrev_b32_e32 v66, 16, v57
	v_and_b32_e32 v67, 0xffff0000, v57
	v_lshlrev_b32_e32 v68, 16, v58
	v_and_b32_e32 v69, 0xffff0000, v58
	v_lshlrev_b32_e32 v70, 16, v59
	v_and_b32_e32 v71, 0xffff0000, v59
	v_mul_f32_e32 v64, v64, v103
	v_mul_f32_e32 v65, v65, v103
	v_mul_f32_e32 v66, v66, v103
	v_mul_f32_e32 v67, v67, v103
	v_mul_f32_e32 v68, v68, v103
	v_mul_f32_e32 v69, v69, v103
	v_mul_f32_e32 v70, v70, v103
	v_mul_f32_e32 v71, v71, v103
	v_pk_mul_f32 v[64:65], v[64:65], v[80:81]
	v_pk_mul_f32 v[66:67], v[66:67], v[82:83]
	v_pk_mul_f32 v[68:69], v[68:69], v[84:85]
	v_pk_mul_f32 v[70:71], v[70:71], v[86:87]
	v_cvt_pk_bf16_f32 v124, v64, v65
	v_cvt_pk_bf16_f32 v125, v66, v67
	v_cvt_pk_bf16_f32 v126, v68, v69
	v_cvt_pk_bf16_f32 v127, v70, v71
	global_store_dwordx4 v[106:107], v[124:127], off
	v_lshlrev_b32_e32 v64, 16, v60
	v_and_b32_e32 v65, 0xffff0000, v60
	v_lshlrev_b32_e32 v66, 16, v61
	v_and_b32_e32 v67, 0xffff0000, v61
	v_lshlrev_b32_e32 v68, 16, v62
	v_and_b32_e32 v69, 0xffff0000, v62
	v_lshlrev_b32_e32 v70, 16, v63
	v_and_b32_e32 v71, 0xffff0000, v63
	v_mul_f32_e32 v64, v64, v103
	v_mul_f32_e32 v65, v65, v103
	v_mul_f32_e32 v66, v66, v103
	v_mul_f32_e32 v67, v67, v103
	v_mul_f32_e32 v68, v68, v103
	v_mul_f32_e32 v69, v69, v103
	v_mul_f32_e32 v70, v70, v103
	v_mul_f32_e32 v71, v71, v103
	v_pk_mul_f32 v[64:65], v[64:65], v[88:89]
	v_pk_mul_f32 v[66:67], v[66:67], v[90:91]
	v_pk_mul_f32 v[68:69], v[68:69], v[92:93]
	v_pk_mul_f32 v[70:71], v[70:71], v[94:95]
	v_cvt_pk_bf16_f32 v124, v64, v65
	v_cvt_pk_bf16_f32 v125, v66, v67
	v_cvt_pk_bf16_f32 v126, v68, v69
	v_cvt_pk_bf16_f32 v127, v70, v71
	global_store_dwordx4 v[106:107], v[124:127], off offset:256
.Lln_end:
	s_movk_i32 s56, 0x1f8
	s_movk_i32 s57, 0x1fff
	s_mov_b32 s58, 0x2c000
	s_mov_b32 s59, 0x84000
	s_mov_b32 s64, 0xb0000
	s_mov_b32 s65, 0xdc000
	s_mov_b64 vcc, s[100:101]
	s_cbranch_vccnz .LBB0_282
	s_branch .Lln_ret
.Lln_latch:
	s_add_i32 s90, s90, 1
	s_mov_b32 s100, 0x42424240
	s_bitcmp1_b32 s100, s90
	s_cbranch_scc0 .Lln_latch_ret
	s_add_i32 s90, s90, 1
	s_branch .Lln_latch_ret

; __global__ void __launch_bounds__(NTHREADS) fwd_megakernel(Params p) {
	.amdhsa_kernel _Z14fwd_megakernel6Params
		.amdhsa_group_segment_fixed_size 0
		.amdhsa_private_segment_fixed_size 0
		.amdhsa_kernarg_size 400
		.amdhsa_user_sgpr_count 2
		.amdhsa_user_sgpr_dispatch_ptr 0
		.amdhsa_user_sgpr_queue_ptr 0
		.amdhsa_user_sgpr_kernarg_segment_ptr 1
		.amdhsa_user_sgpr_dispatch_id 0
		.amdhsa_user_sgpr_kernarg_preload_length 0
		.amdhsa_user_sgpr_kernarg_preload_offset 0
		.amdhsa_user_sgpr_private_segment_size 0
		.amdhsa_uses_dynamic_stack 0
		.amdhsa_enable_private_segment 0
		.amdhsa_system_sgpr_workgroup_id_x 1
		.amdhsa_system_sgpr_workgroup_id_y 0
		.amdhsa_system_sgpr_workgroup_id_z 0
		.amdhsa_system_sgpr_workgroup_info 0
		.amdhsa_system_vgpr_workitem_id 2
		.amdhsa_next_free_vgpr 256
		.amdhsa_next_free_sgpr 102
		.amdhsa_accum_offset 256
		.amdhsa_reserve_vcc 1
		.amdhsa_float_round_mode_32 0
		.amdhsa_float_round_mode_16_64 0
		.amdhsa_float_denorm_mode_32 3
		.amdhsa_float_denorm_mode_16_64 3
		.amdhsa_dx10_clamp 1
		.amdhsa_ieee_mode 1
		.amdhsa_fp16_overflow 0
		.amdhsa_tg_split 0
		.amdhsa_exception_fp_ieee_invalid_op 0
		.amdhsa_exception_fp_denorm_src 0
		.amdhsa_exception_fp_ieee_div_zero 0
		.amdhsa_exception_fp_ieee_overflow 0
		.amdhsa_exception_fp_ieee_underflow 0
		.amdhsa_exception_fp_ieee_inexact 0
		.amdhsa_exception_int_div_zero 0
	.end_amdhsa_kernel

; __global__ void __launch_bounds__(NTHREADS) fwd_megakernel(Params p) {
amdhsa.kernels:
  - .agpr_count:     0
    .args:
      - .offset:         0
        .size:           144
        .value_kind:     by_value
      - .offset:         144
        .size:           4
        .value_kind:     hidden_block_count_x
      - .offset:         148
        .size:           4
        .value_kind:     hidden_block_count_y
      - .offset:         152
        .size:           4
        .value_kind:     hidden_block_count_z
      - .offset:         156
        .size:           2
        .value_kind:     hidden_group_size_x
      - .offset:         158
        .size:           2
        .value_kind:     hidden_group_size_y
      - .offset:         160
        .size:           2
        .value_kind:     hidden_group_size_z
      - .offset:         162
        .size:           2
        .value_kind:     hidden_remainder_x
      - .offset:         164
        .size:           2
        .value_kind:     hidden_remainder_y
      - .offset:         166
        .size:           2
        .value_kind:     hidden_remainder_z
      - .offset:         184
        .size:           8
        .value_kind:     hidden_global_offset_x
      - .offset:         192
        .size:           8
        .value_kind:     hidden_global_offset_y
      - .offset:         200
        .size:           8
        .value_kind:     hidden_global_offset_z
      - .offset:         208
        .size:           2
        .value_kind:     hidden_grid_dims
      - .offset:         232
        .size:           8
        .value_kind:     hidden_multigrid_sync_arg
      - .offset:         264
        .size:           4
        .value_kind:     hidden_dynamic_lds_size
    .group_segment_fixed_size: 0
    .kernarg_segment_align: 8
    .kernarg_segment_size: 400
    .language:       OpenCL C
    .language_version:
      - 2
      - 0
    .max_flat_workgroup_size: 512
    .name:           _Z14fwd_megakernel6Params
    .private_segment_fixed_size: 0
    .sgpr_count:     108
    .sgpr_spill_count: 294
    .symbol:         _Z14fwd_megakernel6Params.kd
    .uniform_work_group_size: 1
    .uses_dynamic_stack: false
    .vgpr_count:     256
    .vgpr_spill_count: 0
    .wavefront_size: 64
